# row-statistics L2 prefetch also in the IN and PG GEMM K-loops
# baseline (speedup 1.0000x reference)
; #define PG8_STAGE(bufoff, gbase, voff) do { _Pragma("unroll") for (int _i = 0; _i < 2; ++_i) \
;         __builtin_amdgcn_global_load_lds((const unsigned*)((const char*)(gbase) + (voff)[_i]), (PG8_LAS unsigned*)(lds + (bufoff) + ldsw + _i * 8192), 16, 0, 0); } while (0)
; #define PG8_LDA(dst, b, h) do { _Pragma("unroll") for (int m = 0; m < 4; ++m) _Pragma("unroll") for (int k = 0; k < 2; ++k) dst[m][k] = *(const PG8_LAS bf16x8*)(lds + PG8_SA(b, h) + aoff + m * 2048 + k * 1024); } while (0)
; #define PG8_LDB(dst, b, h) do { _Pragma("unroll") for (int n = 0; n < 2; ++n) _Pragma("unroll") for (int k = 0; k < 2; ++k) dst[n][k] = *(const PG8_LAS bf16x8*)(lds + PG8_SB(b, h) + boff + n * 2048 + k * 1024); } while (0)
; #define PG8_MMA(ai, bj, At, Bt) do { __builtin_amdgcn_s_setprio(1); _Pragma("unroll") for (int m = 0; m < 4; ++m) _Pragma("unroll") for (int n = 0; n < 2; ++n) _Pragma("unroll") for (int k = 0; k < 2; ++k) \
;         acc[ai][bj][m][n] = __builtin_amdgcn_mfma_f32_16x16x32_bf16(Bt[n][k], At[m][k], acc[ai][bj][m][n], 0, 0, 0); __builtin_amdgcn_s_setprio(0); } while (0)
; #define PG8_WAIT_V(n) asm volatile("s_waitcnt vmcnt(" #n ")" ::: "memory")
; #define PG8_WAIT_L(n) asm volatile("s_waitcnt lgkmcnt(" #n ")" ::: "memory")
; #define PG8_BAR __builtin_amdgcn_s_barrier()
; #define PG8_SCHED __builtin_amdgcn_sched_barrier(0)
; template <class Epi, class Sched, bool ALIGN_EPI = false, bool SP2 = false>
; __device__ __forceinline__ void gemm_phase(PG8_LAS unsigned char* lds, const Gemm g, const Sched& S, const Epi& E) {
;     ...
;             PG8_LDB(B0, 0, 0); PG8_LDB(B1, 0, 1); PG8_SCHED; PG8_LDA(At, 0, 0); PG8_STAGE(PG8_SA(1, 1), a1 + hstep, voffA);
;             PG8_WAIT_V(8); PG8_WAIT_L(0); PG8_BAR; PG8_MMA(0, 0, At, B0); PG8_MMA(0, 1, At, B1); PG8_BAR; PG8_SCHED;
;             PG8_LDA(At, 0, 1); PG8_STAGE(PG8_SB(0, 0), b2, voffB); PG8_STAGE(PG8_SB(0, 1), b2 + hstep, voffB); PG8_STAGE(PG8_SA(0, 0), a2, voffA);
;             PG8_WAIT_V(8); PG8_WAIT_L(0); PG8_BAR; PG8_MMA(1, 0, At, B0); PG8_MMA(1, 1, At, B1); PG8_BAR; PG8_SCHED;
.LBB0_488:
	s_add_i32 s61, s60, 2
	s_add_u32 s62, s78, 0x80
	s_addc_u32 s63, s79, 0
	s_add_i32 s80, 0, 0x10000
	s_cmp_eq_u32 s35, s60
	s_cselect_b32 s71, s43, s63
	s_cselect_b32 s70, s42, s62
	s_cselect_b32 s63, s69, s59
	s_cselect_b32 s62, s68, s58
	s_add_i32 s60, 0, 0x14000
	v_add_u32_e32 v142, s80, v200
	v_add_u32_e32 v178, s60, v200
	ds_read_b128 v[130:133], v142
	ds_read_b128 v[134:137], v142 offset:1024
	ds_read_b128 v[138:141], v142 offset:2048
	ds_read_b128 v[142:145], v142 offset:3072
	ds_read_b128 v[146:149], v178
	ds_read_b128 v[150:153], v178 offset:1024
	ds_read_b128 v[154:157], v178 offset:2048
	ds_read_b128 v[178:181], v178 offset:3072
	v_lshl_add_u64 v[198:199], s[78:79], 0, v[174:175]
	s_add_i32 m0, s7, 0xc000
	ds_read_b128 v[182:185], v202
	ds_read_b128 v[186:189], v202 offset:1024
	ds_read_b128 v[190:193], v202 offset:2048
	ds_read_b128 v[194:197], v202 offset:3072
	ds_read_b128 v[204:207], v202 offset:4096
	ds_read_b128 v[210:213], v202 offset:5120
	ds_read_b128 v[214:217], v202 offset:6144
	ds_read_b128 v[218:221], v202 offset:7168
	global_load_lds_dwordx4 v[198:199], off
	v_lshl_add_u64 v[198:199], s[78:79], 0, v[176:177]
	s_add_i32 m0, s7, 0xe000
	s_nop 0
	global_load_lds_dwordx4 v[198:199], off
	s_waitcnt vmcnt(8)
	s_waitcnt lgkmcnt(0)
	s_barrier
	s_setprio 1
	s_waitcnt lgkmcnt(0)
	v_mfma_f32_16x16x32_bf16 v[126:129], v[130:133], v[182:185], v[126:129]
	v_mfma_f32_16x16x32_bf16 v[122:125], v[138:141], v[182:185], v[122:125]
	v_mfma_f32_16x16x32_bf16 v[110:113], v[130:133], v[190:193], v[110:113]
	v_mfma_f32_16x16x32_bf16 v[106:109], v[138:141], v[190:193], v[106:109]
	v_mfma_f32_16x16x32_bf16 v[94:97], v[130:133], v[204:207], v[94:97]
	v_mfma_f32_16x16x32_bf16 v[90:93], v[138:141], v[204:207], v[90:93]
	v_mfma_f32_16x16x32_bf16 v[78:81], v[130:133], v[214:217], v[78:81]
	v_mfma_f32_16x16x32_bf16 v[74:77], v[138:141], v[214:217], v[74:77]
	v_mfma_f32_16x16x32_bf16 v[126:129], v[134:137], v[186:189], v[126:129]
	v_mfma_f32_16x16x32_bf16 v[122:125], v[142:145], v[186:189], v[122:125]
	v_mfma_f32_16x16x32_bf16 v[110:113], v[134:137], v[194:197], v[110:113]
	v_mfma_f32_16x16x32_bf16 v[106:109], v[142:145], v[194:197], v[106:109]
	v_mfma_f32_16x16x32_bf16 v[94:97], v[134:137], v[210:213], v[94:97]
	v_mfma_f32_16x16x32_bf16 v[90:93], v[142:145], v[210:213], v[90:93]
	v_mfma_f32_16x16x32_bf16 v[78:81], v[134:137], v[218:221], v[78:81]
	v_mfma_f32_16x16x32_bf16 v[74:77], v[142:145], v[218:221], v[74:77]
	s_setprio 0
	s_setprio 1
	v_mfma_f32_16x16x32_bf16 v[118:121], v[146:149], v[182:185], v[118:121]
	v_mfma_f32_16x16x32_bf16 v[114:117], v[154:157], v[182:185], v[114:117]
	v_mfma_f32_16x16x32_bf16 v[102:105], v[146:149], v[190:193], v[102:105]
	v_mfma_f32_16x16x32_bf16 v[98:101], v[154:157], v[190:193], v[98:101]
	v_mfma_f32_16x16x32_bf16 v[86:89], v[146:149], v[204:207], v[86:89]
	v_mfma_f32_16x16x32_bf16 v[82:85], v[154:157], v[204:207], v[82:85]
	v_mfma_f32_16x16x32_bf16 v[70:73], v[146:149], v[214:217], v[70:73]
	v_mfma_f32_16x16x32_bf16 v[66:69], v[154:157], v[214:217], v[66:69]
	v_mfma_f32_16x16x32_bf16 v[118:121], v[150:153], v[186:189], v[118:121]
	v_mfma_f32_16x16x32_bf16 v[114:117], v[178:181], v[186:189], v[114:117]
	v_mfma_f32_16x16x32_bf16 v[102:105], v[150:153], v[194:197], v[102:105]
	v_mfma_f32_16x16x32_bf16 v[98:101], v[178:181], v[194:197], v[98:101]
	v_mfma_f32_16x16x32_bf16 v[86:89], v[150:153], v[210:213], v[86:89]
	v_mfma_f32_16x16x32_bf16 v[82:85], v[178:181], v[210:213], v[82:85]
	v_mfma_f32_16x16x32_bf16 v[70:73], v[150:153], v[218:221], v[70:73]
	v_mfma_f32_16x16x32_bf16 v[66:69], v[178:181], v[218:221], v[66:69]
	s_setprio 0
	s_barrier
	s_add_i32 s80, s80, s6
	v_lshl_add_u64 v[198:199], s[62:63], 0, v[0:1]
	s_mov_b32 m0, s80
	ds_read_b128 v[182:185], v202 offset:16384
	ds_read_b128 v[186:189], v202 offset:17408
	ds_read_b128 v[190:193], v202 offset:18432
	ds_read_b128 v[194:197], v202 offset:19456
	ds_read_b128 v[204:207], v202 offset:20480
	ds_read_b128 v[210:213], v202 offset:21504
	ds_read_b128 v[214:217], v202 offset:22528
	ds_read_b128 v[218:221], v202 offset:23552
	global_load_lds_dwordx4 v[198:199], off
	s_add_i32 m0, s80, 0x2000
	v_lshl_add_u64 v[222:223], s[62:63], 0, v[172:173]
	s_add_u32 s62, s62, s12
	s_addc_u32 s63, s63, s13
	s_add_i32 s60, s60, s6
	global_load_lds_dwordx4 v[222:223], off
	v_lshl_add_u64 v[224:225], s[62:63], 0, v[0:1]
	s_mov_b32 m0, s60
	v_lshl_add_u64 v[226:227], s[62:63], 0, v[172:173]
	global_load_lds_dwordx4 v[224:225], off
	s_add_i32 m0, s60, 0x2000
	v_lshl_add_u64 v[238:239], s[70:71], 0, v[168:169]
	global_load_lds_dwordx4 v[226:227], off
	s_mov_b32 m0, s7
	v_lshl_add_u64 v[240:241], s[70:71], 0, v[170:171]
	global_load_lds_dwordx4 v[238:239], off
	s_mov_b32 m0, s8
	s_nop 0
	global_load_lds_dwordx4 v[240:241], off
	s_waitcnt vmcnt(8)
	s_waitcnt lgkmcnt(0)
	s_barrier
; #define PG8_STAGE(bufoff, gbase, voff) do { _Pragma("unroll") for (int _i = 0; _i < 2; ++_i) \
;         __builtin_amdgcn_global_load_lds((const unsigned*)((const char*)(gbase) + (voff)[_i]), (PG8_LAS unsigned*)(lds + (bufoff) + ldsw + _i * 8192), 16, 0, 0); } while (0)
; #define PG8_LDA(dst, b, h) do { _Pragma("unroll") for (int m = 0; m < 4; ++m) _Pragma("unroll") for (int k = 0; k < 2; ++k) dst[m][k] = *(const PG8_LAS bf16x8*)(lds + PG8_SA(b, h) + aoff + m * 2048 + k * 1024); } while (0)
; #define PG8_LDB(dst, b, h) do { _Pragma("unroll") for (int n = 0; n < 2; ++n) _Pragma("unroll") for (int k = 0; k < 2; ++k) dst[n][k] = *(const PG8_LAS bf16x8*)(lds + PG8_SB(b, h) + boff + n * 2048 + k * 1024); } while (0)
; #define PG8_MMA(ai, bj, At, Bt) do { __builtin_amdgcn_s_setprio(1); _Pragma("unroll") for (int m = 0; m < 4; ++m) _Pragma("unroll") for (int n = 0; n < 2; ++n) _Pragma("unroll") for (int k = 0; k < 2; ++k) \
;         acc[ai][bj][m][n] = __builtin_amdgcn_mfma_f32_16x16x32_bf16(Bt[n][k], At[m][k], acc[ai][bj][m][n], 0, 0, 0); __builtin_amdgcn_s_setprio(0); } while (0)
; #define PG8_WAIT_V(n) asm volatile("s_waitcnt vmcnt(" #n ")" ::: "memory")
; #define PG8_WAIT_L(n) asm volatile("s_waitcnt lgkmcnt(" #n ")" ::: "memory")
; #define PG8_BAR __builtin_amdgcn_s_barrier()
; #define PG8_SCHED __builtin_amdgcn_sched_barrier(0)
; template <class Epi, class Sched, bool ALIGN_EPI = false, bool SP2 = false>
; __device__ __forceinline__ void gemm_phase(PG8_LAS unsigned char* lds, const Gemm g, const Sched& S, const Epi& E) {
;     ...
;             PG8_WAIT_V(8); PG8_WAIT_L(0); PG8_BAR; PG8_MMA(1, 0, At, B0); PG8_MMA(1, 1, At, B1); PG8_BAR; PG8_SCHED;
;             PG8_LDB(B0, 1, 0); PG8_LDB(B1, 1, 1); PG8_SCHED; PG8_LDA(At, 1, 0); PG8_STAGE(PG8_SA(0, 1), a2 + hstep, voffA);
;             PG8_WAIT_V(8); PG8_WAIT_L(0); PG8_BAR; PG8_MMA(0, 0, At, B0); PG8_MMA(0, 1, At, B1); PG8_BAR; PG8_SCHED;
	s_setprio 1
	s_waitcnt lgkmcnt(0)
	v_mfma_f32_16x16x32_bf16 v[62:65], v[130:133], v[182:185], v[62:65]
	v_mfma_f32_16x16x32_bf16 v[58:61], v[138:141], v[182:185], v[58:61]
	v_mfma_f32_16x16x32_bf16 v[46:49], v[130:133], v[190:193], v[46:49]
	v_mfma_f32_16x16x32_bf16 v[42:45], v[138:141], v[190:193], v[42:45]
	v_mfma_f32_16x16x32_bf16 v[30:33], v[130:133], v[204:207], v[30:33]
	v_mfma_f32_16x16x32_bf16 v[26:29], v[138:141], v[204:207], v[26:29]
	v_mfma_f32_16x16x32_bf16 v[14:17], v[130:133], v[214:217], v[14:17]
	v_mfma_f32_16x16x32_bf16 v[10:13], v[138:141], v[214:217], v[10:13]
	v_mfma_f32_16x16x32_bf16 v[62:65], v[134:137], v[186:189], v[62:65]
	v_mfma_f32_16x16x32_bf16 v[58:61], v[142:145], v[186:189], v[58:61]
	v_mfma_f32_16x16x32_bf16 v[46:49], v[134:137], v[194:197], v[46:49]
	v_mfma_f32_16x16x32_bf16 v[42:45], v[142:145], v[194:197], v[42:45]
	v_mfma_f32_16x16x32_bf16 v[30:33], v[134:137], v[210:213], v[30:33]
	v_mfma_f32_16x16x32_bf16 v[26:29], v[142:145], v[210:213], v[26:29]
	v_mfma_f32_16x16x32_bf16 v[14:17], v[134:137], v[218:221], v[14:17]
	v_mfma_f32_16x16x32_bf16 v[10:13], v[142:145], v[218:221], v[10:13]
	s_setprio 0
	s_setprio 1
	v_mfma_f32_16x16x32_bf16 v[54:57], v[146:149], v[182:185], v[54:57]
	v_mfma_f32_16x16x32_bf16 v[50:53], v[154:157], v[182:185], v[50:53]
	v_mfma_f32_16x16x32_bf16 v[38:41], v[146:149], v[190:193], v[38:41]
	v_mfma_f32_16x16x32_bf16 v[34:37], v[154:157], v[190:193], v[34:37]
	v_mfma_f32_16x16x32_bf16 v[22:25], v[146:149], v[204:207], v[22:25]
	v_mfma_f32_16x16x32_bf16 v[18:21], v[154:157], v[204:207], v[18:21]
	v_mfma_f32_16x16x32_bf16 v[6:9], v[146:149], v[214:217], v[6:9]
	v_mfma_f32_16x16x32_bf16 v[2:5], v[154:157], v[214:217], v[2:5]
	v_mfma_f32_16x16x32_bf16 v[54:57], v[150:153], v[186:189], v[54:57]
	v_mfma_f32_16x16x32_bf16 v[50:53], v[178:181], v[186:189], v[50:53]
	v_mfma_f32_16x16x32_bf16 v[38:41], v[150:153], v[194:197], v[38:41]
	v_mfma_f32_16x16x32_bf16 v[34:37], v[178:181], v[194:197], v[34:37]
	v_mfma_f32_16x16x32_bf16 v[22:25], v[150:153], v[210:213], v[22:25]
	v_mfma_f32_16x16x32_bf16 v[18:21], v[178:181], v[210:213], v[18:21]
	v_mfma_f32_16x16x32_bf16 v[6:9], v[150:153], v[218:221], v[6:9]
	v_mfma_f32_16x16x32_bf16 v[2:5], v[178:181], v[218:221], v[2:5]
	s_setprio 0
	s_barrier
	s_add_i32 s60, 0, 0x18000
	s_add_i32 s80, 0, 0x1c000
	v_add_u32_e32 v142, s60, v200
	v_add_u32_e32 v178, s80, v200
	ds_read_b128 v[130:133], v142
	ds_read_b128 v[134:137], v142 offset:1024
	ds_read_b128 v[138:141], v142 offset:2048
	ds_read_b128 v[142:145], v142 offset:3072
	ds_read_b128 v[146:149], v178
	ds_read_b128 v[150:153], v178 offset:1024
	ds_read_b128 v[154:157], v178 offset:2048
	ds_read_b128 v[178:181], v178 offset:3072
	s_add_u32 s62, s70, s12
	s_addc_u32 s63, s71, s13
	s_mov_b32 m0, s9
	v_lshl_add_u64 v[242:243], s[62:63], 0, v[168:169]
	ds_read_b128 v[182:185], v202 offset:32768
	ds_read_b128 v[186:189], v202 offset:33792
	ds_read_b128 v[190:193], v202 offset:34816
	ds_read_b128 v[194:197], v202 offset:35840
	ds_read_b128 v[204:207], v202 offset:36864
	ds_read_b128 v[210:213], v202 offset:37888
	ds_read_b128 v[214:217], v202 offset:38912
	ds_read_b128 v[218:221], v202 offset:39936
	global_load_lds_dwordx4 v[242:243], off
	v_lshl_add_u64 v[242:243], s[62:63], 0, v[170:171]
	s_mov_b32 m0, s30
	s_nop 0
	global_load_lds_dwordx4 v[242:243], off
	s_waitcnt vmcnt(8)
	s_waitcnt lgkmcnt(0)
	s_barrier
	s_setprio 1
	s_waitcnt lgkmcnt(0)
	v_mfma_f32_16x16x32_bf16 v[126:129], v[130:133], v[182:185], v[126:129]
	v_mfma_f32_16x16x32_bf16 v[122:125], v[138:141], v[182:185], v[122:125]
	v_mfma_f32_16x16x32_bf16 v[110:113], v[130:133], v[190:193], v[110:113]
	v_mfma_f32_16x16x32_bf16 v[106:109], v[138:141], v[190:193], v[106:109]
	v_mfma_f32_16x16x32_bf16 v[94:97], v[130:133], v[204:207], v[94:97]
	v_mfma_f32_16x16x32_bf16 v[90:93], v[138:141], v[204:207], v[90:93]
	v_mfma_f32_16x16x32_bf16 v[78:81], v[130:133], v[214:217], v[78:81]
	v_mfma_f32_16x16x32_bf16 v[74:77], v[138:141], v[214:217], v[74:77]
	v_mfma_f32_16x16x32_bf16 v[126:129], v[134:137], v[186:189], v[126:129]
	v_mfma_f32_16x16x32_bf16 v[122:125], v[142:145], v[186:189], v[122:125]
	v_mfma_f32_16x16x32_bf16 v[110:113], v[134:137], v[194:197], v[110:113]
	v_mfma_f32_16x16x32_bf16 v[106:109], v[142:145], v[194:197], v[106:109]
	v_mfma_f32_16x16x32_bf16 v[94:97], v[134:137], v[210:213], v[94:97]
	v_mfma_f32_16x16x32_bf16 v[90:93], v[142:145], v[210:213], v[90:93]
	v_mfma_f32_16x16x32_bf16 v[78:81], v[134:137], v[218:221], v[78:81]
	v_mfma_f32_16x16x32_bf16 v[74:77], v[142:145], v[218:221], v[74:77]
	s_setprio 0
	s_setprio 1
	v_mfma_f32_16x16x32_bf16 v[118:121], v[146:149], v[182:185], v[118:121]
	v_mfma_f32_16x16x32_bf16 v[114:117], v[154:157], v[182:185], v[114:117]
	v_mfma_f32_16x16x32_bf16 v[102:105], v[146:149], v[190:193], v[102:105]
	v_mfma_f32_16x16x32_bf16 v[98:101], v[154:157], v[190:193], v[98:101]
	v_mfma_f32_16x16x32_bf16 v[86:89], v[146:149], v[204:207], v[86:89]
	v_mfma_f32_16x16x32_bf16 v[82:85], v[154:157], v[204:207], v[82:85]
	v_mfma_f32_16x16x32_bf16 v[70:73], v[146:149], v[214:217], v[70:73]
	v_mfma_f32_16x16x32_bf16 v[66:69], v[154:157], v[214:217], v[66:69]
	v_mfma_f32_16x16x32_bf16 v[118:121], v[150:153], v[186:189], v[118:121]
	v_mfma_f32_16x16x32_bf16 v[114:117], v[178:181], v[186:189], v[114:117]
	v_mfma_f32_16x16x32_bf16 v[102:105], v[150:153], v[194:197], v[102:105]
	v_mfma_f32_16x16x32_bf16 v[98:101], v[178:181], v[194:197], v[98:101]
	v_mfma_f32_16x16x32_bf16 v[86:89], v[150:153], v[210:213], v[86:89]
	v_mfma_f32_16x16x32_bf16 v[82:85], v[178:181], v[210:213], v[82:85]
	v_mfma_f32_16x16x32_bf16 v[70:73], v[150:153], v[218:221], v[70:73]
	v_mfma_f32_16x16x32_bf16 v[66:69], v[178:181], v[218:221], v[66:69]
	s_setprio 0
	s_barrier
; #define PG8_STAGE(bufoff, gbase, voff) do { _Pragma("unroll") for (int _i = 0; _i < 2; ++_i) \
;         __builtin_amdgcn_global_load_lds((const unsigned*)((const char*)(gbase) + (voff)[_i]), (PG8_LAS unsigned*)(lds + (bufoff) + ldsw + _i * 8192), 16, 0, 0); } while (0)
; #define PG8_LDA(dst, b, h) do { _Pragma("unroll") for (int m = 0; m < 4; ++m) _Pragma("unroll") for (int k = 0; k < 2; ++k) dst[m][k] = *(const PG8_LAS bf16x8*)(lds + PG8_SA(b, h) + aoff + m * 2048 + k * 1024); } while (0)
; #define PG8_MMA(ai, bj, At, Bt) do { __builtin_amdgcn_s_setprio(1); _Pragma("unroll") for (int m = 0; m < 4; ++m) _Pragma("unroll") for (int n = 0; n < 2; ++n) _Pragma("unroll") for (int k = 0; k < 2; ++k) \
;         acc[ai][bj][m][n] = __builtin_amdgcn_mfma_f32_16x16x32_bf16(Bt[n][k], At[m][k], acc[ai][bj][m][n], 0, 0, 0); __builtin_amdgcn_s_setprio(0); } while (0)
; #define PG8_WAIT_V(n) asm volatile("s_waitcnt vmcnt(" #n ")" ::: "memory")
; #define PG8_WAIT_L(n) asm volatile("s_waitcnt lgkmcnt(" #n ")" ::: "memory")
; #define PG8_BAR __builtin_amdgcn_s_barrier()
; #define PG8_SCHED __builtin_amdgcn_sched_barrier(0)
; template <class Epi, class Sched, bool ALIGN_EPI = false, bool SP2 = false>
; __device__ __forceinline__ void gemm_phase(PG8_LAS unsigned char* lds, const Gemm g, const Sched& S, const Epi& E) {
;     ...
;             PG8_LDA(At, 1, 1); PG8_STAGE(PG8_SB(1, 0), b3, voffB); PG8_STAGE(PG8_SB(1, 1), b3 + hstep, voffB); PG8_STAGE(PG8_SA(1, 0), a3, voffA);
;             PG8_WAIT_V(8); PG8_WAIT_L(0); PG8_BAR; PG8_MMA(1, 0, At, B0); PG8_MMA(1, 1, At, B1); PG8_BAR; PG8_SCHED;
;     __device__ __forceinline__ void operator()(const f32x4 (&acc)[2][2][4][2], const Unit& u, int wr, int wc, int fr, int fq) const {
;     ...
;             for (int m = 0; m < 4; ++m) pp[ai][m] = *(const f32x4*)(rss + (size_t)(row0 + ai * 128 + m * 16) * 4);
	s_add_i32 s60, s60, s6
	v_lshl_add_u64 v[198:199], v[198:199], 0, s[22:23]
	s_mov_b32 m0, s60
	ds_read_b128 v[182:185], v202 offset:49152
	ds_read_b128 v[186:189], v202 offset:50176
	ds_read_b128 v[190:193], v202 offset:51200
	ds_read_b128 v[194:197], v202 offset:52224
	ds_read_b128 v[204:207], v202 offset:53248
	ds_read_b128 v[210:213], v202 offset:54272
	ds_read_b128 v[214:217], v202 offset:55296
	ds_read_b128 v[218:221], v202 offset:56320
	global_load_lds_dwordx4 v[198:199], off
	v_lshl_add_u64 v[198:199], v[222:223], 0, s[22:23]
	s_add_i32 m0, s60, 0x2000
	s_add_i32 s60, s80, s6
	global_load_lds_dwordx4 v[198:199], off
	v_lshl_add_u64 v[198:199], v[224:225], 0, s[22:23]
	s_mov_b32 m0, s60
	s_nop 0
	global_load_lds_dwordx4 v[198:199], off
	v_lshl_add_u64 v[198:199], v[226:227], 0, s[22:23]
	s_add_i32 m0, s60, 0x2000
	s_nop 0
	global_load_lds_dwordx4 v[198:199], off
	v_lshl_add_u64 v[198:199], v[238:239], 0, s[22:23]
	s_mov_b32 m0, s33
	s_nop 0
	global_load_lds_dwordx4 v[198:199], off
	v_lshl_add_u64 v[198:199], v[240:241], 0, s[22:23]
	s_mov_b32 m0, s34
	s_nop 0
	global_load_lds_dwordx4 v[198:199], off
	s_waitcnt vmcnt(8)
	s_waitcnt lgkmcnt(0)
	s_barrier
	s_setprio 1
	s_waitcnt lgkmcnt(0)
	v_mfma_f32_16x16x32_bf16 v[62:65], v[130:133], v[182:185], v[62:65]
	v_mfma_f32_16x16x32_bf16 v[58:61], v[138:141], v[182:185], v[58:61]
	v_mfma_f32_16x16x32_bf16 v[46:49], v[130:133], v[190:193], v[46:49]
	v_mfma_f32_16x16x32_bf16 v[42:45], v[138:141], v[190:193], v[42:45]
	v_mfma_f32_16x16x32_bf16 v[30:33], v[130:133], v[204:207], v[30:33]
	v_mfma_f32_16x16x32_bf16 v[26:29], v[138:141], v[204:207], v[26:29]
	v_mfma_f32_16x16x32_bf16 v[14:17], v[130:133], v[214:217], v[14:17]
	v_mfma_f32_16x16x32_bf16 v[10:13], v[138:141], v[214:217], v[10:13]
	v_mfma_f32_16x16x32_bf16 v[62:65], v[134:137], v[186:189], v[62:65]
	v_mfma_f32_16x16x32_bf16 v[58:61], v[142:145], v[186:189], v[58:61]
	v_mfma_f32_16x16x32_bf16 v[46:49], v[134:137], v[194:197], v[46:49]
	v_mfma_f32_16x16x32_bf16 v[42:45], v[142:145], v[194:197], v[42:45]
	v_mfma_f32_16x16x32_bf16 v[30:33], v[134:137], v[210:213], v[30:33]
	v_mfma_f32_16x16x32_bf16 v[26:29], v[142:145], v[210:213], v[26:29]
	v_mfma_f32_16x16x32_bf16 v[14:17], v[134:137], v[218:221], v[14:17]
	v_mfma_f32_16x16x32_bf16 v[10:13], v[142:145], v[218:221], v[10:13]
	s_setprio 0
	s_setprio 1
	v_mfma_f32_16x16x32_bf16 v[54:57], v[146:149], v[182:185], v[54:57]
	v_mfma_f32_16x16x32_bf16 v[50:53], v[154:157], v[182:185], v[50:53]
	v_mfma_f32_16x16x32_bf16 v[38:41], v[146:149], v[190:193], v[38:41]
	v_mfma_f32_16x16x32_bf16 v[34:37], v[154:157], v[190:193], v[34:37]
	v_mfma_f32_16x16x32_bf16 v[22:25], v[146:149], v[204:207], v[22:25]
	v_mfma_f32_16x16x32_bf16 v[18:21], v[154:157], v[204:207], v[18:21]
	v_mfma_f32_16x16x32_bf16 v[6:9], v[146:149], v[214:217], v[6:9]
	v_mfma_f32_16x16x32_bf16 v[2:5], v[154:157], v[214:217], v[2:5]
	v_mfma_f32_16x16x32_bf16 v[54:57], v[150:153], v[186:189], v[54:57]
	v_mfma_f32_16x16x32_bf16 v[50:53], v[178:181], v[186:189], v[50:53]
	v_mfma_f32_16x16x32_bf16 v[38:41], v[150:153], v[194:197], v[38:41]
	v_mfma_f32_16x16x32_bf16 v[34:37], v[178:181], v[194:197], v[34:37]
	v_mfma_f32_16x16x32_bf16 v[22:25], v[150:153], v[210:213], v[22:25]
	v_mfma_f32_16x16x32_bf16 v[18:21], v[178:181], v[210:213], v[18:21]
	v_mfma_f32_16x16x32_bf16 v[6:9], v[150:153], v[218:221], v[6:9]
	v_mfma_f32_16x16x32_bf16 v[2:5], v[178:181], v[218:221], v[2:5]
	s_setprio 0
	s_barrier
	s_sub_u32 s100, s31, 6
	s_cmp_eq_u32 s60, s100
	s_cbranch_scc0 .Lrs_in
	v_readlane_b32 s100, v251, 12
	v_readlane_b32 s101, v251, 13
	v_and_b32_e32 v255, 63, v158
	v_lshlrev_b32_e32 v255, 6, v255
	v_lshl_add_u32 v254, s57, 12, v255
	s_nop 2
	global_load_dword v254, v254, s[100:101]
.Lrs_in:
	s_add_u32 s78, s78, 0x100
	s_addc_u32 s79, s79, 0
	s_add_u32 s58, s58, 0x100
	s_addc_u32 s59, s59, 0
	s_cmp_ge_i32 s61, s31
	s_mov_b32 s60, s61
	s_cbranch_scc0 .LBB0_488
	v_readlane_b32 s62, v250, 20
	s_mov_b32 s84, s62
	v_readlane_b32 s63, v250, 21

; #define PG8_STAGE(bufoff, gbase, voff) do { _Pragma("unroll") for (int _i = 0; _i < 2; ++_i) \
;         __builtin_amdgcn_global_load_lds((const unsigned*)((const char*)(gbase) + (voff)[_i]), (PG8_LAS unsigned*)(lds + (bufoff) + ldsw + _i * 8192), 16, 0, 0); } while (0)
; #define PG8_LDA(dst, b, h) do { _Pragma("unroll") for (int m = 0; m < 4; ++m) _Pragma("unroll") for (int k = 0; k < 2; ++k) dst[m][k] = *(const PG8_LAS bf16x8*)(lds + PG8_SA(b, h) + aoff + m * 2048 + k * 1024); } while (0)
; #define PG8_LDB(dst, b, h) do { _Pragma("unroll") for (int n = 0; n < 2; ++n) _Pragma("unroll") for (int k = 0; k < 2; ++k) dst[n][k] = *(const PG8_LAS bf16x8*)(lds + PG8_SB(b, h) + boff + n * 2048 + k * 1024); } while (0)
; #define PG8_MMA(ai, bj, At, Bt) do { __builtin_amdgcn_s_setprio(1); _Pragma("unroll") for (int m = 0; m < 4; ++m) _Pragma("unroll") for (int n = 0; n < 2; ++n) _Pragma("unroll") for (int k = 0; k < 2; ++k) \
;         acc[ai][bj][m][n] = __builtin_amdgcn_mfma_f32_16x16x32_bf16(Bt[n][k], At[m][k], acc[ai][bj][m][n], 0, 0, 0); __builtin_amdgcn_s_setprio(0); } while (0)
; #define PG8_WAIT_V(n) asm volatile("s_waitcnt vmcnt(" #n ")" ::: "memory")
; #define PG8_WAIT_L(n) asm volatile("s_waitcnt lgkmcnt(" #n ")" ::: "memory")
; #define PG8_BAR __builtin_amdgcn_s_barrier()
; #define PG8_SCHED __builtin_amdgcn_sched_barrier(0)
; template <class Epi, class Sched, bool ALIGN_EPI = false, bool SP2 = false>
; __device__ __forceinline__ void gemm_phase(PG8_LAS unsigned char* lds, const Gemm g, const Sched& S, const Epi& E) {
;     ...
;             PG8_LDB(B0, 0, 0); PG8_LDB(B1, 0, 1); PG8_SCHED; PG8_LDA(At, 0, 0); PG8_STAGE(PG8_SA(1, 1), a1 + hstep, voffA);
;             PG8_WAIT_V(8); PG8_WAIT_L(0); PG8_BAR; PG8_MMA(0, 0, At, B0); PG8_MMA(0, 1, At, B1); PG8_BAR; PG8_SCHED;
;             PG8_LDA(At, 0, 1); PG8_STAGE(PG8_SB(0, 0), b2, voffB); PG8_STAGE(PG8_SB(0, 1), b2 + hstep, voffB); PG8_STAGE(PG8_SA(0, 0), a2, voffA);
;             PG8_WAIT_V(8); PG8_WAIT_L(0); PG8_BAR; PG8_MMA(1, 0, At, B0); PG8_MMA(1, 1, At, B1); PG8_BAR; PG8_SCHED;
.LBB0_1361:
	s_add_i32 s52, s51, 2
	s_add_u32 s53, s78, 0x80
	s_addc_u32 s54, s79, 0
	s_add_i32 s56, 0, 0x10000
	s_cmp_eq_u32 s9, s51
	s_cselect_b32 s71, s45, s54
	s_cselect_b32 s70, s44, s53
	s_cselect_b32 s55, s69, s50
	s_cselect_b32 s54, s68, s49
	s_add_i32 s51, 0, 0x14000
	v_add_u32_e32 v106, s56, v238
	v_add_u32_e32 v172, s51, v238
	ds_read_b128 v[34:37], v106
	ds_read_b128 v[66:69], v106 offset:1024
	ds_read_b128 v[74:77], v106 offset:2048
	ds_read_b128 v[106:109], v106 offset:3072
	ds_read_b128 v[114:117], v172
	ds_read_b128 v[146:149], v172 offset:1024
	ds_read_b128 v[154:157], v172 offset:2048
	ds_read_b128 v[172:175], v172 offset:3072
	v_lshl_add_u64 v[210:211], s[78:79], 0, v[168:169]
	s_add_i32 m0, s96, 0xc000
	ds_read_b128 v[176:179], v241
	ds_read_b128 v[180:183], v241 offset:1024
	ds_read_b128 v[184:187], v241 offset:2048
	ds_read_b128 v[188:191], v241 offset:3072
	ds_read_b128 v[192:195], v241 offset:4096
	ds_read_b128 v[196:199], v241 offset:5120
	ds_read_b128 v[200:203], v241 offset:6144
	ds_read_b128 v[204:207], v241 offset:7168
	global_load_lds_dwordx4 v[210:211], off
	v_lshl_add_u64 v[210:211], s[78:79], 0, v[170:171]
	s_add_i32 m0, s96, 0xe000
	s_nop 0
	global_load_lds_dwordx4 v[210:211], off
	s_waitcnt vmcnt(8)
	s_waitcnt lgkmcnt(0)
	s_barrier
	s_setprio 1
	s_waitcnt lgkmcnt(0)
	v_mfma_f32_16x16x32_bf16 v[150:153], v[34:37], v[176:179], v[150:153]
	v_mfma_f32_16x16x32_bf16 v[142:145], v[74:77], v[176:179], v[142:145]
	v_mfma_f32_16x16x32_bf16 v[130:133], v[34:37], v[184:187], v[130:133]
	v_mfma_f32_16x16x32_bf16 v[126:129], v[74:77], v[184:187], v[126:129]
	v_mfma_f32_16x16x32_bf16 v[110:113], v[34:37], v[192:195], v[110:113]
	v_mfma_f32_16x16x32_bf16 v[102:105], v[74:77], v[192:195], v[102:105]
	v_mfma_f32_16x16x32_bf16 v[90:93], v[34:37], v[200:203], v[90:93]
	v_mfma_f32_16x16x32_bf16 v[86:89], v[74:77], v[200:203], v[86:89]
	v_mfma_f32_16x16x32_bf16 v[150:153], v[66:69], v[180:183], v[150:153]
	v_mfma_f32_16x16x32_bf16 v[142:145], v[106:109], v[180:183], v[142:145]
	v_mfma_f32_16x16x32_bf16 v[130:133], v[66:69], v[188:191], v[130:133]
	v_mfma_f32_16x16x32_bf16 v[126:129], v[106:109], v[188:191], v[126:129]
	v_mfma_f32_16x16x32_bf16 v[110:113], v[66:69], v[196:199], v[110:113]
	v_mfma_f32_16x16x32_bf16 v[102:105], v[106:109], v[196:199], v[102:105]
	v_mfma_f32_16x16x32_bf16 v[90:93], v[66:69], v[204:207], v[90:93]
	v_mfma_f32_16x16x32_bf16 v[86:89], v[106:109], v[204:207], v[86:89]
	s_setprio 0
	s_setprio 1
	v_mfma_f32_16x16x32_bf16 v[138:141], v[114:117], v[176:179], v[138:141]
	v_mfma_f32_16x16x32_bf16 v[134:137], v[154:157], v[176:179], v[134:137]
	v_mfma_f32_16x16x32_bf16 v[122:125], v[114:117], v[184:187], v[122:125]
	v_mfma_f32_16x16x32_bf16 v[118:121], v[154:157], v[184:187], v[118:121]
	v_mfma_f32_16x16x32_bf16 v[98:101], v[114:117], v[192:195], v[98:101]
	v_mfma_f32_16x16x32_bf16 v[94:97], v[154:157], v[192:195], v[94:97]
	v_mfma_f32_16x16x32_bf16 v[82:85], v[114:117], v[200:203], v[82:85]
	v_mfma_f32_16x16x32_bf16 v[78:81], v[154:157], v[200:203], v[78:81]
	v_mfma_f32_16x16x32_bf16 v[138:141], v[146:149], v[180:183], v[138:141]
	v_mfma_f32_16x16x32_bf16 v[134:137], v[172:175], v[180:183], v[134:137]
	v_mfma_f32_16x16x32_bf16 v[122:125], v[146:149], v[188:191], v[122:125]
	v_mfma_f32_16x16x32_bf16 v[118:121], v[172:175], v[188:191], v[118:121]
	v_mfma_f32_16x16x32_bf16 v[98:101], v[146:149], v[196:199], v[98:101]
	v_mfma_f32_16x16x32_bf16 v[94:97], v[172:175], v[196:199], v[94:97]
	v_mfma_f32_16x16x32_bf16 v[82:85], v[146:149], v[204:207], v[82:85]
	v_mfma_f32_16x16x32_bf16 v[78:81], v[172:175], v[204:207], v[78:81]
	s_setprio 0
	s_barrier
	s_add_i32 s53, s56, s85
	v_lshl_add_u64 v[210:211], s[54:55], 0, v[0:1]
	s_mov_b32 m0, s53
	ds_read_b128 v[176:179], v241 offset:16384
	ds_read_b128 v[180:183], v241 offset:17408
	ds_read_b128 v[184:187], v241 offset:18432
	ds_read_b128 v[188:191], v241 offset:19456
	ds_read_b128 v[192:195], v241 offset:20480
	ds_read_b128 v[196:199], v241 offset:21504
	ds_read_b128 v[200:203], v241 offset:22528
	ds_read_b128 v[204:207], v241 offset:23552
	global_load_lds_dwordx4 v[210:211], off
	s_add_i32 m0, s53, 0x2000
	v_lshl_add_u64 v[212:213], s[54:55], 0, v[166:167]
	s_add_u32 s54, s54, s20
	s_addc_u32 s55, s55, s21
	s_add_i32 s51, s51, s85
	global_load_lds_dwordx4 v[212:213], off
	v_lshl_add_u64 v[214:215], s[54:55], 0, v[0:1]
	s_mov_b32 m0, s51
	v_lshl_add_u64 v[216:217], s[54:55], 0, v[166:167]
	global_load_lds_dwordx4 v[214:215], off
	s_add_i32 m0, s51, 0x2000
	v_lshl_add_u64 v[218:219], s[70:71], 0, v[0:1]
	global_load_lds_dwordx4 v[216:217], off
	s_mov_b32 m0, s96
	v_lshl_add_u64 v[220:221], s[70:71], 0, v[166:167]
	global_load_lds_dwordx4 v[218:219], off
	s_mov_b32 m0, s97
	s_nop 0
	global_load_lds_dwordx4 v[220:221], off
	s_waitcnt vmcnt(8)
	s_waitcnt lgkmcnt(0)
	s_barrier
; #define PG8_STAGE(bufoff, gbase, voff) do { _Pragma("unroll") for (int _i = 0; _i < 2; ++_i) \
;         __builtin_amdgcn_global_load_lds((const unsigned*)((const char*)(gbase) + (voff)[_i]), (PG8_LAS unsigned*)(lds + (bufoff) + ldsw + _i * 8192), 16, 0, 0); } while (0)
; #define PG8_LDA(dst, b, h) do { _Pragma("unroll") for (int m = 0; m < 4; ++m) _Pragma("unroll") for (int k = 0; k < 2; ++k) dst[m][k] = *(const PG8_LAS bf16x8*)(lds + PG8_SA(b, h) + aoff + m * 2048 + k * 1024); } while (0)
; #define PG8_LDB(dst, b, h) do { _Pragma("unroll") for (int n = 0; n < 2; ++n) _Pragma("unroll") for (int k = 0; k < 2; ++k) dst[n][k] = *(const PG8_LAS bf16x8*)(lds + PG8_SB(b, h) + boff + n * 2048 + k * 1024); } while (0)
; #define PG8_MMA(ai, bj, At, Bt) do { __builtin_amdgcn_s_setprio(1); _Pragma("unroll") for (int m = 0; m < 4; ++m) _Pragma("unroll") for (int n = 0; n < 2; ++n) _Pragma("unroll") for (int k = 0; k < 2; ++k) \
;         acc[ai][bj][m][n] = __builtin_amdgcn_mfma_f32_16x16x32_bf16(Bt[n][k], At[m][k], acc[ai][bj][m][n], 0, 0, 0); __builtin_amdgcn_s_setprio(0); } while (0)
; #define PG8_WAIT_V(n) asm volatile("s_waitcnt vmcnt(" #n ")" ::: "memory")
; #define PG8_WAIT_L(n) asm volatile("s_waitcnt lgkmcnt(" #n ")" ::: "memory")
; #define PG8_BAR __builtin_amdgcn_s_barrier()
; #define PG8_SCHED __builtin_amdgcn_sched_barrier(0)
; template <class Epi, class Sched, bool ALIGN_EPI = false, bool SP2 = false>
; __device__ __forceinline__ void gemm_phase(PG8_LAS unsigned char* lds, const Gemm g, const Sched& S, const Epi& E) {
;     ...
;             PG8_WAIT_V(8); PG8_WAIT_L(0); PG8_BAR; PG8_MMA(1, 0, At, B0); PG8_MMA(1, 1, At, B1); PG8_BAR; PG8_SCHED;
;             PG8_LDB(B0, 1, 0); PG8_LDB(B1, 1, 1); PG8_SCHED; PG8_LDA(At, 1, 0); PG8_STAGE(PG8_SA(0, 1), a2 + hstep, voffA);
;             PG8_WAIT_V(8); PG8_WAIT_L(0); PG8_BAR; PG8_MMA(0, 0, At, B0); PG8_MMA(0, 1, At, B1); PG8_BAR; PG8_SCHED;
	s_setprio 1
	s_waitcnt lgkmcnt(0)
	v_mfma_f32_16x16x32_bf16 v[70:73], v[34:37], v[176:179], v[70:73]
	v_mfma_f32_16x16x32_bf16 v[62:65], v[74:77], v[176:179], v[62:65]
	v_mfma_f32_16x16x32_bf16 v[50:53], v[34:37], v[184:187], v[50:53]
	v_mfma_f32_16x16x32_bf16 v[46:49], v[74:77], v[184:187], v[46:49]
	v_mfma_f32_16x16x32_bf16 v[30:33], v[34:37], v[192:195], v[30:33]
	v_mfma_f32_16x16x32_bf16 v[26:29], v[74:77], v[192:195], v[26:29]
	v_mfma_f32_16x16x32_bf16 v[14:17], v[34:37], v[200:203], v[14:17]
	v_mfma_f32_16x16x32_bf16 v[10:13], v[74:77], v[200:203], v[10:13]
	v_mfma_f32_16x16x32_bf16 v[70:73], v[66:69], v[180:183], v[70:73]
	v_mfma_f32_16x16x32_bf16 v[62:65], v[106:109], v[180:183], v[62:65]
	v_mfma_f32_16x16x32_bf16 v[50:53], v[66:69], v[188:191], v[50:53]
	v_mfma_f32_16x16x32_bf16 v[46:49], v[106:109], v[188:191], v[46:49]
	v_mfma_f32_16x16x32_bf16 v[30:33], v[66:69], v[196:199], v[30:33]
	v_mfma_f32_16x16x32_bf16 v[26:29], v[106:109], v[196:199], v[26:29]
	v_mfma_f32_16x16x32_bf16 v[14:17], v[66:69], v[204:207], v[14:17]
	v_mfma_f32_16x16x32_bf16 v[10:13], v[106:109], v[204:207], v[10:13]
	s_setprio 0
	s_setprio 1
	v_mfma_f32_16x16x32_bf16 v[54:57], v[154:157], v[176:179], v[54:57]
	v_mfma_f32_16x16x32_bf16 v[42:45], v[114:117], v[184:187], v[42:45]
	v_mfma_f32_16x16x32_bf16 v[38:41], v[154:157], v[184:187], v[38:41]
	v_mfma_f32_16x16x32_bf16 v[22:25], v[114:117], v[192:195], v[22:25]
	v_mfma_f32_16x16x32_bf16 v[18:21], v[154:157], v[192:195], v[18:21]
	v_mfma_f32_16x16x32_bf16 v[6:9], v[114:117], v[200:203], v[6:9]
	v_mfma_f32_16x16x32_bf16 v[2:5], v[154:157], v[200:203], v[2:5]
	v_mfma_f32_16x16x32_bf16 v[34:37], v[114:117], v[176:179], v[58:61]
	v_mfma_f32_16x16x32_bf16 v[54:57], v[172:175], v[180:183], v[54:57]
	v_mfma_f32_16x16x32_bf16 v[42:45], v[146:149], v[188:191], v[42:45]
	v_mfma_f32_16x16x32_bf16 v[38:41], v[172:175], v[188:191], v[38:41]
	v_mfma_f32_16x16x32_bf16 v[22:25], v[146:149], v[196:199], v[22:25]
	v_mfma_f32_16x16x32_bf16 v[18:21], v[172:175], v[196:199], v[18:21]
	v_mfma_f32_16x16x32_bf16 v[6:9], v[146:149], v[204:207], v[6:9]
	v_mfma_f32_16x16x32_bf16 v[2:5], v[172:175], v[204:207], v[2:5]
	v_mfma_f32_16x16x32_bf16 v[34:37], v[146:149], v[180:183], v[34:37]
	s_setprio 0
	s_barrier
	s_add_i32 s51, 0, 0x18000
	s_add_i32 s53, 0, 0x1c000
	v_add_u32_e32 v106, s51, v238
	v_add_u32_e32 v172, s53, v238
	ds_read_b128 v[58:61], v106
	ds_read_b128 v[66:69], v106 offset:1024
	ds_read_b128 v[74:77], v106 offset:2048
	ds_read_b128 v[106:109], v106 offset:3072
	ds_read_b128 v[114:117], v172
	ds_read_b128 v[146:149], v172 offset:1024
	ds_read_b128 v[154:157], v172 offset:2048
	ds_read_b128 v[172:175], v172 offset:3072
	s_add_u32 s54, s70, s20
	s_addc_u32 s55, s71, s21
	s_mov_b32 m0, s0
	v_lshl_add_u64 v[222:223], s[54:55], 0, v[0:1]
	ds_read_b128 v[176:179], v241 offset:32768
	ds_read_b128 v[180:183], v241 offset:33792
	ds_read_b128 v[184:187], v241 offset:34816
	ds_read_b128 v[188:191], v241 offset:35840
	ds_read_b128 v[192:195], v241 offset:36864
	ds_read_b128 v[196:199], v241 offset:37888
	ds_read_b128 v[200:203], v241 offset:38912
	ds_read_b128 v[204:207], v241 offset:39936
	global_load_lds_dwordx4 v[222:223], off
	v_lshl_add_u64 v[222:223], s[54:55], 0, v[166:167]
	s_mov_b32 m0, s1
	s_nop 0
	global_load_lds_dwordx4 v[222:223], off
	s_waitcnt vmcnt(8)
	s_waitcnt lgkmcnt(0)
	s_barrier
	s_setprio 1
	s_waitcnt lgkmcnt(0)
	v_mfma_f32_16x16x32_bf16 v[150:153], v[58:61], v[176:179], v[150:153]
	v_mfma_f32_16x16x32_bf16 v[142:145], v[74:77], v[176:179], v[142:145]
	v_mfma_f32_16x16x32_bf16 v[130:133], v[58:61], v[184:187], v[130:133]
	v_mfma_f32_16x16x32_bf16 v[126:129], v[74:77], v[184:187], v[126:129]
	v_mfma_f32_16x16x32_bf16 v[110:113], v[58:61], v[192:195], v[110:113]
	v_mfma_f32_16x16x32_bf16 v[102:105], v[74:77], v[192:195], v[102:105]
	v_mfma_f32_16x16x32_bf16 v[90:93], v[58:61], v[200:203], v[90:93]
	v_mfma_f32_16x16x32_bf16 v[86:89], v[74:77], v[200:203], v[86:89]
	v_mfma_f32_16x16x32_bf16 v[150:153], v[66:69], v[180:183], v[150:153]
	v_mfma_f32_16x16x32_bf16 v[142:145], v[106:109], v[180:183], v[142:145]
	v_mfma_f32_16x16x32_bf16 v[130:133], v[66:69], v[188:191], v[130:133]
	v_mfma_f32_16x16x32_bf16 v[126:129], v[106:109], v[188:191], v[126:129]
	v_mfma_f32_16x16x32_bf16 v[110:113], v[66:69], v[196:199], v[110:113]
	v_mfma_f32_16x16x32_bf16 v[102:105], v[106:109], v[196:199], v[102:105]
	v_mfma_f32_16x16x32_bf16 v[90:93], v[66:69], v[204:207], v[90:93]
	v_mfma_f32_16x16x32_bf16 v[86:89], v[106:109], v[204:207], v[86:89]
	s_setprio 0
	s_setprio 1
	v_mfma_f32_16x16x32_bf16 v[138:141], v[114:117], v[176:179], v[138:141]
	v_mfma_f32_16x16x32_bf16 v[134:137], v[154:157], v[176:179], v[134:137]
	v_mfma_f32_16x16x32_bf16 v[122:125], v[114:117], v[184:187], v[122:125]
	v_mfma_f32_16x16x32_bf16 v[118:121], v[154:157], v[184:187], v[118:121]
	v_mfma_f32_16x16x32_bf16 v[98:101], v[114:117], v[192:195], v[98:101]
	v_mfma_f32_16x16x32_bf16 v[94:97], v[154:157], v[192:195], v[94:97]
	v_mfma_f32_16x16x32_bf16 v[82:85], v[114:117], v[200:203], v[82:85]
	v_mfma_f32_16x16x32_bf16 v[78:81], v[154:157], v[200:203], v[78:81]
	v_mfma_f32_16x16x32_bf16 v[138:141], v[146:149], v[180:183], v[138:141]
	v_mfma_f32_16x16x32_bf16 v[134:137], v[172:175], v[180:183], v[134:137]
	v_mfma_f32_16x16x32_bf16 v[122:125], v[146:149], v[188:191], v[122:125]
	v_mfma_f32_16x16x32_bf16 v[118:121], v[172:175], v[188:191], v[118:121]
	v_mfma_f32_16x16x32_bf16 v[98:101], v[146:149], v[196:199], v[98:101]
	v_mfma_f32_16x16x32_bf16 v[94:97], v[172:175], v[196:199], v[94:97]
	v_mfma_f32_16x16x32_bf16 v[82:85], v[146:149], v[204:207], v[82:85]
	v_mfma_f32_16x16x32_bf16 v[78:81], v[172:175], v[204:207], v[78:81]
	s_setprio 0
	s_barrier
; #define PG8_STAGE(bufoff, gbase, voff) do { _Pragma("unroll") for (int _i = 0; _i < 2; ++_i) \
;         __builtin_amdgcn_global_load_lds((const unsigned*)((const char*)(gbase) + (voff)[_i]), (PG8_LAS unsigned*)(lds + (bufoff) + ldsw + _i * 8192), 16, 0, 0); } while (0)
; #define PG8_LDA(dst, b, h) do { _Pragma("unroll") for (int m = 0; m < 4; ++m) _Pragma("unroll") for (int k = 0; k < 2; ++k) dst[m][k] = *(const PG8_LAS bf16x8*)(lds + PG8_SA(b, h) + aoff + m * 2048 + k * 1024); } while (0)
; #define PG8_MMA(ai, bj, At, Bt) do { __builtin_amdgcn_s_setprio(1); _Pragma("unroll") for (int m = 0; m < 4; ++m) _Pragma("unroll") for (int n = 0; n < 2; ++n) _Pragma("unroll") for (int k = 0; k < 2; ++k) \
;         acc[ai][bj][m][n] = __builtin_amdgcn_mfma_f32_16x16x32_bf16(Bt[n][k], At[m][k], acc[ai][bj][m][n], 0, 0, 0); __builtin_amdgcn_s_setprio(0); } while (0)
; #define PG8_WAIT_V(n) asm volatile("s_waitcnt vmcnt(" #n ")" ::: "memory")
; #define PG8_WAIT_L(n) asm volatile("s_waitcnt lgkmcnt(" #n ")" ::: "memory")
; #define PG8_BAR __builtin_amdgcn_s_barrier()
; #define PG8_SCHED __builtin_amdgcn_sched_barrier(0)
; template <class Epi, class Sched, bool ALIGN_EPI = false, bool SP2 = false>
; __device__ __forceinline__ void gemm_phase(PG8_LAS unsigned char* lds, const Gemm g, const Sched& S, const Epi& E) {
;     ...
;             PG8_LDA(At, 1, 1); PG8_STAGE(PG8_SB(1, 0), b3, voffB); PG8_STAGE(PG8_SB(1, 1), b3 + hstep, voffB); PG8_STAGE(PG8_SA(1, 0), a3, voffA);
;             PG8_WAIT_V(8); PG8_WAIT_L(0); PG8_BAR; PG8_MMA(1, 0, At, B0); PG8_MMA(1, 1, At, B1); PG8_BAR; PG8_SCHED;
;     __device__ __forceinline__ void operator()(const f32x4 (&acc)[2][2][4][2], const Unit& u, int wr, int wc, int fr, int fq) const {
;     ...
;           for (int g = 0; g < 8; ++g) pp[g] = *(const f32x4*)(rss + (size_t)(row0 + (g >> 2) * 128 + (g & 3) * 16) * 4);
	s_add_i32 s51, s51, s85
	v_lshl_add_u64 v[210:211], v[210:211], 0, s[22:23]
	s_mov_b32 m0, s51
	ds_read_b128 v[176:179], v241 offset:49152
	ds_read_b128 v[180:183], v241 offset:50176
	ds_read_b128 v[184:187], v241 offset:51200
	ds_read_b128 v[188:191], v241 offset:52224
	ds_read_b128 v[192:195], v241 offset:53248
	ds_read_b128 v[196:199], v241 offset:54272
	ds_read_b128 v[200:203], v241 offset:55296
	ds_read_b128 v[204:207], v241 offset:56320
	global_load_lds_dwordx4 v[210:211], off
	v_lshl_add_u64 v[210:211], v[212:213], 0, s[22:23]
	s_add_i32 m0, s51, 0x2000
	s_add_i32 s51, s53, s85
	global_load_lds_dwordx4 v[210:211], off
	v_lshl_add_u64 v[210:211], v[214:215], 0, s[22:23]
	s_mov_b32 m0, s51
	s_nop 0
	global_load_lds_dwordx4 v[210:211], off
	v_lshl_add_u64 v[210:211], v[216:217], 0, s[22:23]
	s_add_i32 m0, s51, 0x2000
	s_nop 0
	global_load_lds_dwordx4 v[210:211], off
	v_lshl_add_u64 v[210:211], v[218:219], 0, s[22:23]
	s_mov_b32 m0, s7
	s_nop 0
	global_load_lds_dwordx4 v[210:211], off
	v_lshl_add_u64 v[210:211], v[220:221], 0, s[22:23]
	s_mov_b32 m0, s8
	s_nop 0
	global_load_lds_dwordx4 v[210:211], off
	s_waitcnt vmcnt(8)
	s_waitcnt lgkmcnt(0)
	s_barrier
	s_setprio 1
	s_waitcnt lgkmcnt(0)
	v_mfma_f32_16x16x32_bf16 v[70:73], v[58:61], v[176:179], v[70:73]
	v_mfma_f32_16x16x32_bf16 v[62:65], v[74:77], v[176:179], v[62:65]
	v_mfma_f32_16x16x32_bf16 v[50:53], v[58:61], v[184:187], v[50:53]
	v_mfma_f32_16x16x32_bf16 v[46:49], v[74:77], v[184:187], v[46:49]
	v_mfma_f32_16x16x32_bf16 v[30:33], v[58:61], v[192:195], v[30:33]
	v_mfma_f32_16x16x32_bf16 v[26:29], v[74:77], v[192:195], v[26:29]
	v_mfma_f32_16x16x32_bf16 v[14:17], v[58:61], v[200:203], v[14:17]
	v_mfma_f32_16x16x32_bf16 v[10:13], v[74:77], v[200:203], v[10:13]
	v_mfma_f32_16x16x32_bf16 v[70:73], v[66:69], v[180:183], v[70:73]
	v_mfma_f32_16x16x32_bf16 v[62:65], v[106:109], v[180:183], v[62:65]
	v_mfma_f32_16x16x32_bf16 v[50:53], v[66:69], v[188:191], v[50:53]
	v_mfma_f32_16x16x32_bf16 v[46:49], v[106:109], v[188:191], v[46:49]
	v_mfma_f32_16x16x32_bf16 v[30:33], v[66:69], v[196:199], v[30:33]
	v_mfma_f32_16x16x32_bf16 v[26:29], v[106:109], v[196:199], v[26:29]
	v_mfma_f32_16x16x32_bf16 v[14:17], v[66:69], v[204:207], v[14:17]
	v_mfma_f32_16x16x32_bf16 v[10:13], v[106:109], v[204:207], v[10:13]
	s_setprio 0
	s_setprio 1
	v_mfma_f32_16x16x32_bf16 v[34:37], v[114:117], v[176:179], v[34:37]
	v_mfma_f32_16x16x32_bf16 v[58:61], v[146:149], v[180:183], v[34:37]
	v_mfma_f32_16x16x32_bf16 v[34:37], v[154:157], v[176:179], v[54:57]
	v_mfma_f32_16x16x32_bf16 v[54:57], v[172:175], v[180:183], v[34:37]
	v_mfma_f32_16x16x32_bf16 v[34:37], v[114:117], v[184:187], v[42:45]
	v_mfma_f32_16x16x32_bf16 v[42:45], v[146:149], v[188:191], v[34:37]
	v_mfma_f32_16x16x32_bf16 v[34:37], v[154:157], v[184:187], v[38:41]
	v_mfma_f32_16x16x32_bf16 v[22:25], v[114:117], v[192:195], v[22:25]
	v_mfma_f32_16x16x32_bf16 v[18:21], v[154:157], v[192:195], v[18:21]
	v_mfma_f32_16x16x32_bf16 v[6:9], v[114:117], v[200:203], v[6:9]
	v_mfma_f32_16x16x32_bf16 v[2:5], v[154:157], v[200:203], v[2:5]
	v_mfma_f32_16x16x32_bf16 v[38:41], v[172:175], v[188:191], v[34:37]
	v_mfma_f32_16x16x32_bf16 v[22:25], v[146:149], v[196:199], v[22:25]
	v_mfma_f32_16x16x32_bf16 v[18:21], v[172:175], v[196:199], v[18:21]
	v_mfma_f32_16x16x32_bf16 v[6:9], v[146:149], v[204:207], v[6:9]
	v_mfma_f32_16x16x32_bf16 v[2:5], v[172:175], v[204:207], v[2:5]
	s_setprio 0
	s_barrier
	s_sub_u32 s100, s6, 6
	s_cmp_eq_u32 s51, s100
	s_cbranch_scc0 .Lrs_pg
	v_readlane_b32 s100, v251, 12
	v_readlane_b32 s101, v251, 13
	v_and_b32_e32 v255, 63, v158
	v_lshlrev_b32_e32 v255, 6, v255
	v_lshl_add_u32 v254, s19, 12, v255
	s_nop 2
	global_load_dword v254, v254, s[100:101]
.Lrs_pg:
	s_add_u32 s78, s78, 0x100
	s_addc_u32 s79, s79, 0
	s_add_u32 s49, s49, 0x100
	s_addc_u32 s50, s50, 0
	s_cmp_ge_i32 s52, s6
	s_mov_b32 s51, s52
	s_cbranch_scc0 .LBB0_1361
